# combined: DSA loop with conflict-free V pitch, K-fragment reads first behind the barrier, depth-8 LDS fragment prefetch, K/V tile loads two tiles ahead; IDX score loop wait counts loads only
# speedup vs baseline: 1.0053x; 1.0053x over previous
; #define LAS __attribute__((address_space(3)))
; #define LDS_WAIT() asm volatile("s_waitcnt lgkmcnt(0)" ::: "memory")
; __device__ __forceinline__ void dsa_unit(const bf16* QB, const int* SEL, bf16* AO, int b, int kvh, int t, LAS unsigned char* wl, int lane) {
;     ...
;     int sidx[8];
; #pragma unroll
;     for (int kb = 0; kb < 8; ++kb) { const int p = 32 * kb + n; sidx[kb] = (p < nsel) ? SEL[row * 256 + p] : 0; }
;     bf16x8 qf[4];
;     { const bf16* qp = QB + row * NBP + CQ + (kvh * 4 + (l15 & 3)) * 128 + 8 * kq;
; #pragma unroll
;       for (int ks = 0; ks < 4; ++ks) qf[ks] = *(const bf16x8*)(qp + 32 * ks); }
;     if (hi == 0) {
; #pragma unroll
;         for (int kb = 0; kb < 8; ++kb) il[32 * kb + n] = sidx[kb];
;     }
;     LDS_WAIT();
;     const int r4 = kq, c16 = l15;
;     const bf16* kg = QB + rowbase * NBP + CK + kvh * 128 + c16 * 8;
;     const bf16* vg = QB + rowbase * NBP + CV + kvh * 128 + c16 * 8;
;     bf16x8 kr[3][8];
; #pragma unroll
;     for (int pb = 0; pb < 3; ++pb)
; #pragma unroll
;         for (int i = 0; i < 8; ++i) kr[pb][i] = *(const bf16x8*)(kg + (size_t)il[32 * pb + 4 * i + r4] * NBP);
;     float lg[8][4];
;     float mx[4] = {-__builtin_inff(), -__builtin_inff(), -__builtin_inff(), -__builtin_inff()};
;     LAS unsigned char* kdst = buf + r4 * 272 + c16 * 16;
;     const LAS unsigned char* kfb = buf + l15 * 272 + 16 * kq;
;     const bool upper = (lane >> 4) & 1;
.Ldsa_selld_end:
	v_mov_b32_e32 v64, 0
	v_mov_b32_e32 v65, 0
	v_mov_b32_e32 v66, 0
	v_mov_b32_e32 v67, 0
	v_lshlrev_b32_e32 v179, 6, v206
	s_lshl_b32 s24, s0, 12
	s_add_u32 s24, s24, 0x12800
	v_add_u32_e32 v179, s24, v179
	ds_write_b128 v179, v[64:67] offset:0
	ds_write_b128 v179, v[64:67] offset:16
	ds_write_b128 v179, v[64:67] offset:32
	ds_write_b128 v179, v[64:67] offset:48
	v_lshrrev_b32_e32 v178, 4, v207
	v_add_u32_e32 v178, s4, v178
	v_and_b32_e32 v179, 15, v207
	v_lshlrev_b32_e32 v182, 4, v179
	s_lshl_b32 s24, s5, 8
	s_add_u32 s24, s24, 0x1000
	v_add_u32_e32 v182, s24, v182
	v_lshl_add_u64 v[160:161], s[78:79], 0, v[182:183]
	v_mad_u64_u32 v[160:161], s[12:13], v178, s23, v[160:161]
	s_mov_b32 s24, 0x44000
	s_mov_b32 s25, 0
	v_lshl_add_u64 v[162:163], v[160:161], 0, s[24:25]
	global_load_dwordx4 v[144:147], v[160:161], off
	global_load_dwordx4 v[148:151], v[160:161], off offset:1024
	global_load_dwordx4 v[152:155], v[162:163], off
	global_load_dwordx4 v[156:159], v[162:163], off offset:1024
	s_cmp_gt_u32 s8, 1
	s_cselect_b32 s24, s16, 0
	v_lshl_add_u64 v[160:161], v[160:161], 0, s[24:25]
	v_lshl_add_u64 v[162:163], v[162:163], 0, s[24:25]
	v_and_b32_e32 v64, 31, v206
	v_lshrrev_b32_e32 v65, 2, v64
	v_and_b32_e32 v66, 3, v64
	s_add_u32 s24, s44, s7
	s_add_u32 s24, s24, s4
	v_add_u32_e32 v178, s24, v65
	s_lshl_b32 s25, s5, 2
	v_add_u32_e32 v179, s25, v66
	v_lshlrev_b32_e32 v179, 8, v179
	v_lshl_add_u32 v182, v175, 1, v179
	v_lshl_add_u64 v[128:129], s[78:79], 0, v[182:183]
	v_mad_u64_u32 v[128:129], s[12:13], v178, s23, v[128:129]
	global_load_dwordx4 v[80:83], v[128:129], off offset:0
	global_load_dwordx4 v[84:87], v[128:129], off offset:32
	global_load_dwordx4 v[88:91], v[128:129], off offset:64
	global_load_dwordx4 v[92:95], v[128:129], off offset:96
	global_load_dwordx4 v[96:99], v[128:129], off offset:128
	global_load_dwordx4 v[100:103], v[128:129], off offset:160
	global_load_dwordx4 v[104:107], v[128:129], off offset:192
	global_load_dwordx4 v[108:111], v[128:129], off offset:224
	v_add_u32_e32 v178, s44, v65
	v_lshlrev_b32_e32 v172, 9, v178
	v_add_u32_e32 v172, 0x12800, v172
	s_add_u32 s24, s44, s7
	v_add_u32_e32 v178, s24, v65
	v_sub_u32_e32 v178, v175, v178
	v_add_u32_e32 v178, 0x80, v178
	v_lshlrev_b32_e32 v178, 2, v178
	v_lshl_add_u32 v177, v66, 10, v178
	v_add_u32_e32 v177, 0x1b400, v177
	s_sub_u32 s19, s24, 0x7a
	s_lshl_b32 s25, s5, 2
	v_add_u32_e32 v178, s25, v66
	v_lshlrev_b32_e32 v178, 7, v178
	v_add_u32_e32 v176, 0x1a83c, v178
	ds_read_b32 v176, v176
	v_and_b32_e32 v64, 0xff, v207
	v_subrev_u32_e32 v65, 0x80, v64
	v_sub_u32_e32 v66, 0, v65
	v_max_i32_e32 v66, v65, v66
	v_mov_b32_e32 v67, 8
	v_cmp_le_i32_e32 vcc, 12, v66
	s_nop 1
	v_addc_co_u32_e32 v67, vcc, 0, v67, vcc
	v_cmp_le_i32_e32 vcc, 16, v66
	s_nop 1
	v_addc_co_u32_e32 v67, vcc, 0, v67, vcc
	v_cmp_le_i32_e32 vcc, 23, v66
	s_nop 1
	v_addc_co_u32_e32 v67, vcc, 0, v67, vcc
	v_cmp_le_i32_e32 vcc, 32, v66
	s_nop 1
	v_addc_co_u32_e32 v67, vcc, 0, v67, vcc
	v_cmp_le_i32_e32 vcc, 46, v66
	s_nop 1
	v_addc_co_u32_e32 v67, vcc, 0, v67, vcc
	v_cmp_le_i32_e32 vcc, 64, v66
	s_nop 1
	v_addc_co_u32_e32 v67, vcc, 0, v67, vcc
	v_cmp_le_i32_e32 vcc, 91, v66
	s_nop 1
	v_addc_co_u32_e32 v67, vcc, 0, v67, vcc
	v_cmp_gt_i32_e32 vcc, 8, v66
	s_nop 1
	v_cndmask_b32_e32 v67, v67, v66, vcc
	v_add_u32_e32 v68, 16, v67
	v_cmp_lt_i32_e32 vcc, 0, v65
	s_nop 1
	v_cndmask_b32_e32 v67, v67, v68, vcc
	v_lshrrev_b32_e32 v68, 8, v207
	s_lshl_b32 s24, s5, 2
	v_add_u32_e32 v69, s24, v68
	v_lshl_add_u32 v69, v69, 5, v67
	v_lshlrev_b32_e32 v69, 2, v69
	v_add_u32_e32 v69, 0x1a800, v69
	ds_read_b32 v70, v69
	ds_read_b32 v71, v69 offset:256
	v_lshl_add_u32 v72, v68, 8, v64
	v_lshlrev_b32_e32 v72, 2, v72
	v_add_u32_e32 v72, 0x1b400, v72
	s_waitcnt lgkmcnt(0)
	ds_write_b32 v72, v70
	ds_write_b32 v72, v71 offset:2048
	s_waitcnt vmcnt(0)
	global_load_dwordx4 v[214:217], v[160:161], off
	global_load_dwordx4 v[218:221], v[160:161], off offset:1024
	global_load_dwordx4 v[222:225], v[162:163], off
	global_load_dwordx4 v[226:229], v[162:163], off offset:1024
	s_mov_b32 s41, 0
	s_cmp_gt_u32 s8, 2
	s_cselect_b32 s40, s16, 0
	v_lshl_add_u64 v[160:161], v[160:161], 0, s[40:41]
	v_lshl_add_u64 v[162:163], v[162:163], 0, s[40:41]
	s_lshl_b32 s24, s0, 12
	s_add_u32 s24, s24, 0x12800
	v_lshrrev_b32_e32 v64, 3, v0
	v_and_b32_e32 v64, 0x1fc, v64
	v_add_u32_e32 v64, s24, v64
	v_lshlrev_b32_e64 v65, v0, 1
	ds_or_b32 v64, v65 offset:0
	v_lshrrev_b32_e32 v64, 3, v1
	v_and_b32_e32 v64, 0x1fc, v64
	v_add_u32_e32 v64, s24, v64
	v_lshlrev_b32_e64 v65, v1, 1
	ds_or_b32 v64, v65 offset:512
	v_lshrrev_b32_e32 v64, 3, v2
	v_and_b32_e32 v64, 0x1fc, v64
	v_add_u32_e32 v64, s24, v64
	v_lshlrev_b32_e64 v65, v2, 1
	ds_or_b32 v64, v65 offset:1024
	v_lshrrev_b32_e32 v64, 3, v3
	v_and_b32_e32 v64, 0x1fc, v64
	v_add_u32_e32 v64, s24, v64
	v_lshlrev_b32_e64 v65, v3, 1
	ds_or_b32 v64, v65 offset:1536
	v_lshrrev_b32_e32 v64, 3, v4
	v_and_b32_e32 v64, 0x1fc, v64
	v_add_u32_e32 v64, s24, v64
	v_lshlrev_b32_e64 v65, v4, 1
	ds_or_b32 v64, v65 offset:2048
	v_lshrrev_b32_e32 v64, 3, v5
	v_and_b32_e32 v64, 0x1fc, v64
	v_add_u32_e32 v64, s24, v64
	v_lshlrev_b32_e64 v65, v5, 1
	ds_or_b32 v64, v65 offset:2560
	v_lshrrev_b32_e32 v64, 3, v6
	v_and_b32_e32 v64, 0x1fc, v64
	v_add_u32_e32 v64, s24, v64
	v_lshlrev_b32_e64 v65, v6, 1
	ds_or_b32 v64, v65 offset:3072
	v_lshrrev_b32_e32 v64, 3, v7
	v_and_b32_e32 v64, 0x1fc, v64
	v_add_u32_e32 v64, s24, v64
	v_lshlrev_b32_e64 v65, v7, 1
	ds_or_b32 v64, v65 offset:3584
	s_cmp_gt_u32 s43, 1
	s_cbranch_scc0 .Ldsa_selor_end
; __device__ __forceinline__ void dsa_unit(const bf16* QB, const int* SEL, bf16* AO, int b, int kvh, int t, LAS unsigned char* wl, int lane) {
;     ...
;     int sidx[8];
; #pragma unroll
;     for (int kb = 0; kb < 8; ++kb) { const int p = 32 * kb + n; sidx[kb] = (p < nsel) ? SEL[row * 256 + p] : 0; }
;     bf16x8 qf[4];
;     { const bf16* qp = QB + row * NBP + CQ + (kvh * 4 + (l15 & 3)) * 128 + 8 * kq;
; #pragma unroll
;       for (int ks = 0; ks < 4; ++ks) qf[ks] = *(const bf16x8*)(qp + 32 * ks); }
;     if (hi == 0) {
; #pragma unroll
;         for (int kb = 0; kb < 8; ++kb) il[32 * kb + n] = sidx[kb];
;     }
	v_lshrrev_b32_e32 v64, 3, v8
	v_and_b32_e32 v64, 0x1fc, v64
	v_add_u32_e32 v64, s24, v64
	v_lshlrev_b32_e64 v65, v8, 1
	ds_or_b32 v64, v65 offset:0
	v_lshrrev_b32_e32 v64, 3, v9
	v_and_b32_e32 v64, 0x1fc, v64
	v_add_u32_e32 v64, s24, v64
	v_lshlrev_b32_e64 v65, v9, 1
	ds_or_b32 v64, v65 offset:512
	v_lshrrev_b32_e32 v64, 3, v10
	v_and_b32_e32 v64, 0x1fc, v64
	v_add_u32_e32 v64, s24, v64
	v_lshlrev_b32_e64 v65, v10, 1
	ds_or_b32 v64, v65 offset:1024
	v_lshrrev_b32_e32 v64, 3, v11
	v_and_b32_e32 v64, 0x1fc, v64
	v_add_u32_e32 v64, s24, v64
	v_lshlrev_b32_e64 v65, v11, 1
	ds_or_b32 v64, v65 offset:1536
	v_lshrrev_b32_e32 v64, 3, v12
	v_and_b32_e32 v64, 0x1fc, v64
	v_add_u32_e32 v64, s24, v64
	v_lshlrev_b32_e64 v65, v12, 1
	ds_or_b32 v64, v65 offset:2048
	v_lshrrev_b32_e32 v64, 3, v13
	v_and_b32_e32 v64, 0x1fc, v64
	v_add_u32_e32 v64, s24, v64
	v_lshlrev_b32_e64 v65, v13, 1
	ds_or_b32 v64, v65 offset:2560
	v_lshrrev_b32_e32 v64, 3, v14
	v_and_b32_e32 v64, 0x1fc, v64
	v_add_u32_e32 v64, s24, v64
	v_lshlrev_b32_e64 v65, v14, 1
	ds_or_b32 v64, v65 offset:3072
	v_lshrrev_b32_e32 v64, 3, v15
	v_and_b32_e32 v64, 0x1fc, v64
	v_add_u32_e32 v64, s24, v64
	v_lshlrev_b32_e64 v65, v15, 1
	ds_or_b32 v64, v65 offset:3584
	s_cmp_gt_u32 s43, 2
	s_cbranch_scc0 .Ldsa_selor_end
	v_lshrrev_b32_e32 v64, 3, v16
	v_and_b32_e32 v64, 0x1fc, v64
	v_add_u32_e32 v64, s24, v64
	v_lshlrev_b32_e64 v65, v16, 1
	ds_or_b32 v64, v65 offset:0
	v_lshrrev_b32_e32 v64, 3, v17
	v_and_b32_e32 v64, 0x1fc, v64
	v_add_u32_e32 v64, s24, v64
	v_lshlrev_b32_e64 v65, v17, 1
	ds_or_b32 v64, v65 offset:512
	v_lshrrev_b32_e32 v64, 3, v18
	v_and_b32_e32 v64, 0x1fc, v64
	v_add_u32_e32 v64, s24, v64
	v_lshlrev_b32_e64 v65, v18, 1
	ds_or_b32 v64, v65 offset:1024
	v_lshrrev_b32_e32 v64, 3, v19
	v_and_b32_e32 v64, 0x1fc, v64
	v_add_u32_e32 v64, s24, v64
	v_lshlrev_b32_e64 v65, v19, 1
	ds_or_b32 v64, v65 offset:1536
	v_lshrrev_b32_e32 v64, 3, v20
	v_and_b32_e32 v64, 0x1fc, v64
	v_add_u32_e32 v64, s24, v64
	v_lshlrev_b32_e64 v65, v20, 1
	ds_or_b32 v64, v65 offset:2048
	v_lshrrev_b32_e32 v64, 3, v21
	v_and_b32_e32 v64, 0x1fc, v64
	v_add_u32_e32 v64, s24, v64
	v_lshlrev_b32_e64 v65, v21, 1
	ds_or_b32 v64, v65 offset:2560
	v_lshrrev_b32_e32 v64, 3, v22
	v_and_b32_e32 v64, 0x1fc, v64
	v_add_u32_e32 v64, s24, v64
	v_lshlrev_b32_e64 v65, v22, 1
	ds_or_b32 v64, v65 offset:3072
	v_lshrrev_b32_e32 v64, 3, v23
	v_and_b32_e32 v64, 0x1fc, v64
	v_add_u32_e32 v64, s24, v64
	v_lshlrev_b32_e64 v65, v23, 1
	ds_or_b32 v64, v65 offset:3584
	s_cmp_gt_u32 s43, 3
	s_cbranch_scc0 .Ldsa_selor_end
	v_lshrrev_b32_e32 v64, 3, v24
	v_and_b32_e32 v64, 0x1fc, v64
	v_add_u32_e32 v64, s24, v64
	v_lshlrev_b32_e64 v65, v24, 1
	ds_or_b32 v64, v65 offset:0
	v_lshrrev_b32_e32 v64, 3, v25
	v_and_b32_e32 v64, 0x1fc, v64
	v_add_u32_e32 v64, s24, v64
	v_lshlrev_b32_e64 v65, v25, 1
	ds_or_b32 v64, v65 offset:512
	v_lshrrev_b32_e32 v64, 3, v26
	v_and_b32_e32 v64, 0x1fc, v64
	v_add_u32_e32 v64, s24, v64
	v_lshlrev_b32_e64 v65, v26, 1
	ds_or_b32 v64, v65 offset:1024
	v_lshrrev_b32_e32 v64, 3, v27
	v_and_b32_e32 v64, 0x1fc, v64
	v_add_u32_e32 v64, s24, v64
	v_lshlrev_b32_e64 v65, v27, 1
	ds_or_b32 v64, v65 offset:1536
	v_lshrrev_b32_e32 v64, 3, v28
	v_and_b32_e32 v64, 0x1fc, v64
	v_add_u32_e32 v64, s24, v64
	v_lshlrev_b32_e64 v65, v28, 1
	ds_or_b32 v64, v65 offset:2048
	v_lshrrev_b32_e32 v64, 3, v29
	v_and_b32_e32 v64, 0x1fc, v64
	v_add_u32_e32 v64, s24, v64
	v_lshlrev_b32_e64 v65, v29, 1
	ds_or_b32 v64, v65 offset:2560
	v_lshrrev_b32_e32 v64, 3, v30
	v_and_b32_e32 v64, 0x1fc, v64
	v_add_u32_e32 v64, s24, v64
	v_lshlrev_b32_e64 v65, v30, 1
	ds_or_b32 v64, v65 offset:3072
	v_lshrrev_b32_e32 v64, 3, v31
	v_and_b32_e32 v64, 0x1fc, v64
	v_add_u32_e32 v64, s24, v64
	v_lshlrev_b32_e64 v65, v31, 1
	ds_or_b32 v64, v65 offset:3584

; #define LAS __attribute__((address_space(3)))
; #define LDS_WAIT() asm volatile("s_waitcnt lgkmcnt(0)" ::: "memory")
; __device__ __forceinline__ void dsa_unit(const bf16* QB, const int* SEL, bf16* AO, int b, int kvh, int t, LAS unsigned char* wl, int lane) {
;     ...
; #pragma unroll
;     for (int kb = 0; kb < 8; ++kb) {
; #pragma unroll
;         for (int i = 0; i < 8; ++i) *(LAS bf16x8*)(kdst + (4 * i) * 272) = kr[kb % 3][i];
;         if (kb + 3 < 8) {
; #pragma unroll
;             for (int i = 0; i < 8; ++i) kr[kb % 3][i] = *(const bf16x8*)(kg + (size_t)il[32 * (kb + 3) + 4 * i + r4] * NBP);
;         }
;         LDS_WAIT();
;         f32x4v a0 = {0.f, 0.f, 0.f, 0.f}, a1 = {0.f, 0.f, 0.f, 0.f};
; #pragma unroll
;         for (int ks = 0; ks < 4; ++ks) { const bf16x8 b0 = *(const LAS bf16x8*)(kfb + 64 * ks), b1 = *(const LAS bf16x8*)(kfb + 16 * 272 + 64 * ks);
;             a0 = __builtin_amdgcn_mfma_f32_16x16x32_bf16(qf[ks], b0, a0, 0, 0, 0); a1 = __builtin_amdgcn_mfma_f32_16x16x32_bf16(qf[ks], b1, a1, 0, 0, 0); }
;         LDS_WAIT();
;         const int bk = t5_bucket(sidx[kb] - t);
;         const bool valid = (32 * kb + n) < nsel;
; #pragma unroll
;         for (int g = 0; g < 4; ++g) { const float raw = upper ? a1[g] : a0[g]; const float v = valid ? raw + bl[g * 32 + bk] : -__builtin_inff(); lg[kb][g] = v; mx[g] = __builtin_fmaxf(mx[g], v); }
;     }
.Ldsa_it:
	v_add_u32_e32 v168, s10, v164
	ds_read_b128 v[112:115], v168 offset:0
	ds_read_b128 v[116:119], v168 offset:32
	ds_read_b128 v[120:123], v168 offset:64
	ds_read_b128 v[124:127], v168 offset:96
	ds_read_b128 v[188:191], v168 offset:128
	ds_read_b128 v[192:195], v168 offset:160
	ds_read_b128 v[196:199], v168 offset:192
	ds_read_b128 v[200:203], v168 offset:224
	v_add_u32_e32 v169, s10, v165
	v_add_u32_e32 v170, s11, v166
	v_add_u32_e32 v171, s11, v167
	s_add_u32 s24, s9, 1
	s_lshl_b32 s20, s9, 6
	s_add_u32 s27, s20, 32
	v_lshrrev_b32_e32 v182, v175, v182
	s_cmp_le_i32 s20, s19
	s_cbranch_scc1 .Ldsa_farA0
	s_lshl_b32 s26, s20, 2
	v_add_u32_e32 v179, s26, v177
	ds_read_b32 v64, v179 offset:0
	ds_read_b32 v65, v179 offset:4
	ds_read_b32 v66, v179 offset:8
	ds_read_b32 v67, v179 offset:12
	ds_read_b32 v68, v179 offset:16
	ds_read_b32 v69, v179 offset:20
	ds_read_b32 v70, v179 offset:24
	ds_read_b32 v71, v179 offset:28
	ds_read_b32 v72, v179 offset:64
	ds_read_b32 v73, v179 offset:68
	ds_read_b32 v74, v179 offset:72
	ds_read_b32 v75, v179 offset:76
	ds_read_b32 v76, v179 offset:80
	ds_read_b32 v77, v179 offset:84
	ds_read_b32 v78, v179 offset:88
	ds_read_b32 v79, v179 offset:92
	s_waitcnt lgkmcnt(0)
	v_bfe_i32 v178, v174, 0, 1
	v_bfi_b32 v64, v178, v64, s13
	v_bfe_i32 v178, v174, 1, 1
	v_bfi_b32 v65, v178, v65, s13
	v_bfe_i32 v178, v174, 2, 1
	v_bfi_b32 v66, v178, v66, s13
	v_bfe_i32 v178, v174, 3, 1
	v_bfi_b32 v67, v178, v67, s13
	v_bfe_i32 v178, v174, 4, 1
	v_bfi_b32 v68, v178, v68, s13
	v_bfe_i32 v178, v174, 5, 1
	v_bfi_b32 v69, v178, v69, s13
	v_bfe_i32 v178, v174, 6, 1
	v_bfi_b32 v70, v178, v70, s13
	v_bfe_i32 v178, v174, 7, 1
	v_bfi_b32 v71, v178, v71, s13
	v_bfe_i32 v178, v174, 16, 1
	v_bfi_b32 v72, v178, v72, s13
	v_bfe_i32 v178, v174, 17, 1
	v_bfi_b32 v73, v178, v73, s13
	v_bfe_i32 v178, v174, 18, 1
	v_bfi_b32 v74, v178, v74, s13
	v_bfe_i32 v178, v174, 19, 1
	v_bfi_b32 v75, v178, v75, s13
	v_bfe_i32 v178, v174, 20, 1
	v_bfi_b32 v76, v178, v76, s13
	v_bfe_i32 v178, v174, 21, 1
	v_bfi_b32 v77, v178, v77, s13
	v_bfe_i32 v178, v174, 22, 1
	v_bfi_b32 v78, v178, v78, s13
	v_bfe_i32 v178, v174, 23, 1
	v_bfi_b32 v79, v178, v79, s13
	s_nop 1
.Ldsa_farA0:
	s_waitcnt lgkmcnt(7)
	v_mfma_f32_32x32x16_bf16 v[64:79], v[112:115], v[80:83], v[64:79]
	ds_read_b128 v[112:115], v168 offset:8704
	v_bfe_i32 v178, v182, 0, 1
	v_bfi_b32 v128, v178, v176, s13
	v_bfe_i32 v179, v182, 1, 1
	v_bfi_b32 v129, v179, v176, s13
	s_waitcnt lgkmcnt(7)
	v_mfma_f32_32x32x16_bf16 v[64:79], v[116:119], v[84:87], v[64:79]
	ds_read_b128 v[116:119], v168 offset:8736
	v_bfe_i32 v178, v182, 2, 1
	v_bfi_b32 v130, v178, v176, s13
	v_bfe_i32 v179, v182, 3, 1
	v_bfi_b32 v131, v179, v176, s13
	global_load_dwordx4 v[144:147], v[160:161], off
	s_waitcnt lgkmcnt(7)
	v_mfma_f32_32x32x16_bf16 v[64:79], v[120:123], v[88:91], v[64:79]
	ds_read_b128 v[120:123], v168 offset:8768
	v_bfe_i32 v178, v182, 4, 1
	v_bfi_b32 v132, v178, v176, s13
	v_bfe_i32 v179, v182, 5, 1
	v_bfi_b32 v133, v179, v176, s13
	global_load_dwordx4 v[148:151], v[160:161], off offset:1024
	s_waitcnt lgkmcnt(7)
	v_mfma_f32_32x32x16_bf16 v[64:79], v[124:127], v[92:95], v[64:79]
	ds_read_b128 v[124:127], v168 offset:8800
	v_bfe_i32 v178, v182, 6, 1
	v_bfi_b32 v134, v178, v176, s13
	v_bfe_i32 v179, v182, 7, 1
	v_bfi_b32 v135, v179, v176, s13
	global_load_dwordx4 v[152:155], v[162:163], off
	s_waitcnt lgkmcnt(7)
	v_mfma_f32_32x32x16_bf16 v[64:79], v[188:191], v[96:99], v[64:79]
	ds_read_b128 v[188:191], v168 offset:8832
	v_bfe_i32 v178, v182, 16, 1
	v_bfi_b32 v136, v178, v176, s13
	v_bfe_i32 v179, v182, 17, 1
	v_bfi_b32 v137, v179, v176, s13
	global_load_dwordx4 v[156:159], v[162:163], off offset:1024
	s_waitcnt lgkmcnt(7)
	v_mfma_f32_32x32x16_bf16 v[64:79], v[192:195], v[100:103], v[64:79]
	ds_read_b128 v[192:195], v168 offset:8864
	v_bfe_i32 v178, v182, 18, 1
	v_bfi_b32 v138, v178, v176, s13
	v_bfe_i32 v179, v182, 19, 1
	v_bfi_b32 v139, v179, v176, s13
	s_add_u32 s40, s9, 3
	s_cmp_lt_u32 s40, s8
	s_cselect_b32 s40, s16, 0
	v_lshl_add_u64 v[160:161], v[160:161], 0, s[40:41]
	v_lshl_add_u64 v[162:163], v[162:163], 0, s[40:41]
	s_waitcnt lgkmcnt(7)
	v_mfma_f32_32x32x16_bf16 v[64:79], v[196:199], v[104:107], v[64:79]
	ds_read_b128 v[196:199], v168 offset:8896
	v_bfe_i32 v178, v182, 20, 1
	v_bfi_b32 v140, v178, v176, s13
	v_bfe_i32 v179, v182, 21, 1
	v_bfi_b32 v141, v179, v176, s13
	s_waitcnt lgkmcnt(7)
	v_mfma_f32_32x32x16_bf16 v[64:79], v[200:203], v[108:111], v[64:79]
	ds_read_b128 v[200:203], v168 offset:8928
	v_bfe_i32 v178, v182, 22, 1
	v_bfi_b32 v142, v178, v176, s13
	v_bfe_i32 v179, v182, 23, 1
	v_bfi_b32 v143, v179, v176, s13
	s_cmp_le_i32 s27, s19
	s_cbranch_scc1 .Ldsa_farB0
	s_lshl_b32 s26, s27, 2
	v_add_u32_e32 v179, s26, v177
	ds_read_b32 v128, v179 offset:0
	ds_read_b32 v129, v179 offset:4
	ds_read_b32 v130, v179 offset:8
	ds_read_b32 v131, v179 offset:12
	ds_read_b32 v132, v179 offset:16
	ds_read_b32 v133, v179 offset:20
	ds_read_b32 v134, v179 offset:24
	ds_read_b32 v135, v179 offset:28
	ds_read_b32 v136, v179 offset:64
	ds_read_b32 v137, v179 offset:68
	ds_read_b32 v138, v179 offset:72
	ds_read_b32 v139, v179 offset:76
	ds_read_b32 v140, v179 offset:80
	ds_read_b32 v141, v179 offset:84
	ds_read_b32 v142, v179 offset:88
	ds_read_b32 v143, v179 offset:92
	s_waitcnt lgkmcnt(0)
	v_bfe_i32 v178, v182, 0, 1
	v_bfi_b32 v128, v178, v128, s13
	v_bfe_i32 v178, v182, 1, 1
	v_bfi_b32 v129, v178, v129, s13
	v_bfe_i32 v178, v182, 2, 1
	v_bfi_b32 v130, v178, v130, s13
	v_bfe_i32 v178, v182, 3, 1
	v_bfi_b32 v131, v178, v131, s13
	v_bfe_i32 v178, v182, 4, 1
	v_bfi_b32 v132, v178, v132, s13
	v_bfe_i32 v178, v182, 5, 1
	v_bfi_b32 v133, v178, v133, s13
	v_bfe_i32 v178, v182, 6, 1
	v_bfi_b32 v134, v178, v134, s13
	v_bfe_i32 v178, v182, 7, 1
	v_bfi_b32 v135, v178, v135, s13
	v_bfe_i32 v178, v182, 16, 1
	v_bfi_b32 v136, v178, v136, s13
	v_bfe_i32 v178, v182, 17, 1
	v_bfi_b32 v137, v178, v137, s13
	v_bfe_i32 v178, v182, 18, 1
	v_bfi_b32 v138, v178, v138, s13
	v_bfe_i32 v178, v182, 19, 1
	v_bfi_b32 v139, v178, v139, s13
	v_bfe_i32 v178, v182, 20, 1
	v_bfi_b32 v140, v178, v140, s13
	v_bfe_i32 v178, v182, 21, 1
	v_bfi_b32 v141, v178, v141, s13
	v_bfe_i32 v178, v182, 22, 1
	v_bfi_b32 v142, v178, v142, s13
	v_bfe_i32 v178, v182, 23, 1
	v_bfi_b32 v143, v178, v143, s13
	s_nop 1
; #define LAS __attribute__((address_space(3)))
; #define LDS_WAIT() asm volatile("s_waitcnt lgkmcnt(0)" ::: "memory")
; __device__ __forceinline__ void dsa_unit(const bf16* QB, const int* SEL, bf16* AO, int b, int kvh, int t, LAS unsigned char* wl, int lane) {
;     ...
;         for (int ks = 0; ks < 4; ++ks) { const bf16x8 b0 = *(const LAS bf16x8*)(kfb + 64 * ks), b1 = *(const LAS bf16x8*)(kfb + 16 * 272 + 64 * ks);
;             a0 = __builtin_amdgcn_mfma_f32_16x16x32_bf16(qf[ks], b0, a0, 0, 0, 0); a1 = __builtin_amdgcn_mfma_f32_16x16x32_bf16(qf[ks], b1, a1, 0, 0, 0); }
;         LDS_WAIT();
;         const int bk = t5_bucket(sidx[kb] - t);
;         const bool valid = (32 * kb + n) < nsel;
; #pragma unroll
;         for (int g = 0; g < 4; ++g) { const float raw = upper ? a1[g] : a0[g]; const float v = valid ? raw + bl[g * 32 + bk] : -__builtin_inff(); lg[kb][g] = v; mx[g] = __builtin_fmaxf(mx[g], v); }
;     }
;     bf16x8 vr[3][8];
; #pragma unroll
;     for (int pb = 0; pb < 3; ++pb)
; #pragma unroll
;         for (int i = 0; i < 8; ++i) vr[pb][i] = *(const bf16x8*)(vg + (size_t)il[32 * pb + 4 * i + r4] * NBP);
; #pragma unroll
;     for (int g = 0; g < 4; ++g) {
;         float m = mx[g];
;         m = __builtin_fmaxf(m, __shfl_xor(m, 1)); m = __builtin_fmaxf(m, __shfl_xor(m, 2)); m = __builtin_fmaxf(m, __shfl_xor(m, 4)); m = __builtin_fmaxf(m, __shfl_xor(m, 8)); m = __builtin_fmaxf(m, __shfl_xor(m, 16));
;         float s = 0.f;
; #pragma unroll
;         for (int kb = 0; kb < 8; ++kb) { const float e = __builtin_amdgcn_exp2f(lg[kb][g] - m); lg[kb][g] = e; s += e; }
;     ...
;     for (int ch = 0; ch < 8; ++ch) {
; #pragma unroll
;         for (int i = 0; i < 8; ++i) *(LAS bf16x8*)(vdst + (4 * i) * 288) = vr[ch % 3][i];
;         if (ch + 3 < 8) {
; #pragma unroll
;             for (int i = 0; i < 8; ++i) vr[ch % 3][i] = *(const bf16x8*)(vg + (size_t)il[32 * (ch + 3) + 4 * i + r4] * NBP);
;         }
;         const bf16x8 pf = *(const LAS bf16x8*)(pfp + 32 * ch);
;         LDS_WAIT();
; #pragma unroll
;         for (int c = 0; c < 8; ++c) {
;             const s16x4 lo = vtr(vtb + c * 32), hh = vtr(vtb + 4 * 288 + c * 32);
;             o[c] = __builtin_amdgcn_mfma_f32_16x16x32_bf16(pf, (bf16x8){lo[0], lo[1], lo[2], lo[3], hh[0], hh[1], hh[2], hh[3]}, o[c], 0, 0, 0);
;         }
;         LDS_WAIT();
;     }
.Ldsa_farB0:
	ds_read_b32 v174, v172 offset:8
	ds_read_b32 v182, v172 offset:12
	s_nop 1
	s_waitcnt lgkmcnt(9)
	v_mfma_f32_32x32x16_bf16 v[128:143], v[112:115], v[80:83], v[128:143]
	ds_read_b64_tr_b16 v[112:113], v169 offset:0
	ds_read_b64_tr_b16 v[114:115], v169 offset:1280
	v_exp_f32_e32 v64, v64
	v_exp_f32_e32 v65, v65
	v_add_f32_e32 v173, v173, v64
	v_add_f32_e32 v173, v173, v65
	v_cvt_pk_bf16_f32 v64, v64, v65
	s_waitcnt lgkmcnt(10)
	v_mfma_f32_32x32x16_bf16 v[128:143], v[116:119], v[84:87], v[128:143]
	ds_read_b64_tr_b16 v[116:117], v169 offset:64
	ds_read_b64_tr_b16 v[118:119], v169 offset:1344
	v_exp_f32_e32 v66, v66
	v_exp_f32_e32 v67, v67
	v_add_f32_e32 v173, v173, v66
	v_add_f32_e32 v173, v173, v67
	v_cvt_pk_bf16_f32 v65, v66, v67
	s_waitcnt lgkmcnt(11)
	v_mfma_f32_32x32x16_bf16 v[128:143], v[120:123], v[88:91], v[128:143]
	ds_read_b64_tr_b16 v[120:121], v169 offset:128
	ds_read_b64_tr_b16 v[122:123], v169 offset:1408
	v_exp_f32_e32 v68, v68
	v_exp_f32_e32 v69, v69
	v_add_f32_e32 v173, v173, v68
	v_add_f32_e32 v173, v173, v69
	v_cvt_pk_bf16_f32 v66, v68, v69
	s_waitcnt lgkmcnt(12)
	v_mfma_f32_32x32x16_bf16 v[128:143], v[124:127], v[92:95], v[128:143]
	ds_read_b64_tr_b16 v[124:125], v169 offset:192
	ds_read_b64_tr_b16 v[126:127], v169 offset:1472
	v_exp_f32_e32 v70, v70
	v_exp_f32_e32 v71, v71
	v_add_f32_e32 v173, v173, v70
	v_add_f32_e32 v173, v173, v71
	v_cvt_pk_bf16_f32 v67, v70, v71
	s_waitcnt lgkmcnt(13)
	v_mfma_f32_32x32x16_bf16 v[128:143], v[188:191], v[96:99], v[128:143]
	ds_read_b64_tr_b16 v[188:189], v169 offset:5120
	ds_read_b64_tr_b16 v[190:191], v169 offset:6400
	v_exp_f32_e32 v72, v72
	v_exp_f32_e32 v73, v73
	v_add_f32_e32 v173, v173, v72
	v_add_f32_e32 v173, v173, v73
	v_cvt_pk_bf16_f32 v68, v72, v73
	s_waitcnt lgkmcnt(14)
	v_mfma_f32_32x32x16_bf16 v[128:143], v[192:195], v[100:103], v[128:143]
	ds_read_b64_tr_b16 v[192:193], v169 offset:5184
	ds_read_b64_tr_b16 v[194:195], v169 offset:6464
	v_exp_f32_e32 v74, v74
	v_exp_f32_e32 v75, v75
	v_add_f32_e32 v173, v173, v74
	v_add_f32_e32 v173, v173, v75
	v_cvt_pk_bf16_f32 v69, v74, v75
	s_waitcnt lgkmcnt(15)
	v_mfma_f32_32x32x16_bf16 v[128:143], v[196:199], v[104:107], v[128:143]
	ds_read_b64_tr_b16 v[196:197], v169 offset:5248
	ds_read_b64_tr_b16 v[198:199], v169 offset:6528
	v_exp_f32_e32 v76, v76
	v_exp_f32_e32 v77, v77
	v_add_f32_e32 v173, v173, v76
	v_add_f32_e32 v173, v173, v77
	v_cvt_pk_bf16_f32 v70, v76, v77
	s_waitcnt lgkmcnt(15)
	v_mfma_f32_32x32x16_bf16 v[128:143], v[200:203], v[108:111], v[128:143]
	ds_read_b64_tr_b16 v[200:201], v169 offset:5312
	ds_read_b64_tr_b16 v[202:203], v169 offset:6592
	v_exp_f32_e32 v78, v78
	v_exp_f32_e32 v79, v79
	v_add_f32_e32 v173, v173, v78
	v_add_f32_e32 v173, v173, v79
	v_cvt_pk_bf16_f32 v71, v78, v79
	s_waitcnt lgkmcnt(14)
	v_mfma_f32_32x32x16_bf16 v[0:15], v[64:67], v[112:115], v[0:15]
	ds_read_b64_tr_b16 v[112:113], v169 offset:10240
	ds_read_b64_tr_b16 v[114:115], v169 offset:11520
	s_waitcnt vmcnt(4)
	ds_write_b128 v170, v[214:217]
	v_exp_f32_e32 v128, v128
	v_exp_f32_e32 v129, v129
	v_add_f32_e32 v173, v173, v128
	v_add_f32_e32 v173, v173, v129
	v_cvt_pk_bf16_f32 v128, v128, v129
	s_waitcnt lgkmcnt(15)
	v_mfma_f32_32x32x16_bf16 v[16:31], v[64:67], v[116:119], v[16:31]
	ds_read_b64_tr_b16 v[116:117], v169 offset:10304
	ds_read_b64_tr_b16 v[118:119], v169 offset:11584
	ds_write_b128 v171, v[218:221]
	v_exp_f32_e32 v130, v130
	v_exp_f32_e32 v131, v131
	v_add_f32_e32 v173, v173, v130
	v_add_f32_e32 v173, v173, v131
	v_cvt_pk_bf16_f32 v129, v130, v131
	s_waitcnt lgkmcnt(15)
	v_mfma_f32_32x32x16_bf16 v[32:47], v[64:67], v[120:123], v[32:47]
	ds_read_b64_tr_b16 v[120:121], v169 offset:10368
	ds_read_b64_tr_b16 v[122:123], v169 offset:11648
	ds_write_b128 v170, v[222:225] offset:8704
	v_exp_f32_e32 v132, v132
	v_exp_f32_e32 v133, v133
	v_add_f32_e32 v173, v173, v132
	v_add_f32_e32 v173, v173, v133
	v_cvt_pk_bf16_f32 v130, v132, v133
	s_waitcnt lgkmcnt(15)
	v_mfma_f32_32x32x16_bf16 v[48:63], v[64:67], v[124:127], v[48:63]
	ds_read_b64_tr_b16 v[124:125], v169 offset:10432
	ds_read_b64_tr_b16 v[126:127], v169 offset:11712
	ds_write_b128 v171, v[226:229] offset:10240
	v_exp_f32_e32 v134, v134
	v_exp_f32_e32 v135, v135
	v_add_f32_e32 v173, v173, v134
	v_add_f32_e32 v173, v173, v135
	v_cvt_pk_bf16_f32 v131, v134, v135
	v_mfma_f32_32x32x16_bf16 v[0:15], v[68:71], v[188:191], v[0:15]
	ds_read_b64_tr_b16 v[188:189], v169 offset:15360
	ds_read_b64_tr_b16 v[190:191], v169 offset:16640
	s_nop 0
	v_exp_f32_e32 v136, v136
	v_exp_f32_e32 v137, v137
	v_add_f32_e32 v173, v173, v136
	v_add_f32_e32 v173, v173, v137
	v_cvt_pk_bf16_f32 v132, v136, v137
	s_waitcnt lgkmcnt(15)
	v_mfma_f32_32x32x16_bf16 v[16:31], v[68:71], v[192:195], v[16:31]
	ds_read_b64_tr_b16 v[192:193], v169 offset:15424
	ds_read_b64_tr_b16 v[194:195], v169 offset:16704
	s_nop 0
	v_exp_f32_e32 v138, v138
	v_exp_f32_e32 v139, v139
	v_add_f32_e32 v173, v173, v138
	v_add_f32_e32 v173, v173, v139
	v_cvt_pk_bf16_f32 v133, v138, v139
	v_mfma_f32_32x32x16_bf16 v[32:47], v[68:71], v[196:199], v[32:47]
	ds_read_b64_tr_b16 v[196:197], v169 offset:15488
	ds_read_b64_tr_b16 v[198:199], v169 offset:16768
	s_nop 0
	v_exp_f32_e32 v140, v140
	v_exp_f32_e32 v141, v141
	v_add_f32_e32 v173, v173, v140
	v_add_f32_e32 v173, v173, v141
	v_cvt_pk_bf16_f32 v134, v140, v141
	s_waitcnt lgkmcnt(15)
	v_mfma_f32_32x32x16_bf16 v[48:63], v[68:71], v[200:203], v[48:63]
	ds_read_b64_tr_b16 v[200:201], v169 offset:15552
	ds_read_b64_tr_b16 v[202:203], v169 offset:16832
	s_nop 0
	v_exp_f32_e32 v142, v142
	v_exp_f32_e32 v143, v143
	v_add_f32_e32 v173, v173, v142
	v_add_f32_e32 v173, v173, v143
	v_cvt_pk_bf16_f32 v135, v142, v143
	v_lshrrev_b32_e32 v174, v175, v174
	v_mfma_f32_32x32x16_bf16 v[0:15], v[128:131], v[112:115], v[0:15]
	v_bfe_i32 v178, v174, 0, 1
	v_bfi_b32 v64, v178, v176, s13
	v_bfe_i32 v179, v174, 1, 1
	v_bfi_b32 v65, v179, v176, s13
	s_waitcnt lgkmcnt(15)
; #define LAS __attribute__((address_space(3)))
; #define LDS_WAIT() asm volatile("s_waitcnt lgkmcnt(0)" ::: "memory")
; __device__ __forceinline__ s16x4 vtr(const LAS unsigned char* p) { return __builtin_bit_cast(s16x4, __builtin_amdgcn_ds_read_tr16_b64_v4i16((LAS s16x4*)p)); }
; __device__ __forceinline__ void dsa_unit(const bf16* QB, const int* SEL, bf16* AO, int b, int kvh, int t, LAS unsigned char* wl, int lane) {
;     ...
; #pragma unroll
;     for (int kb = 0; kb < 8; ++kb) {
; #pragma unroll
;         for (int i = 0; i < 8; ++i) *(LAS bf16x8*)(kdst + (4 * i) * 272) = kr[kb % 3][i];
;         if (kb + 3 < 8) {
; #pragma unroll
;             for (int i = 0; i < 8; ++i) kr[kb % 3][i] = *(const bf16x8*)(kg + (size_t)il[32 * (kb + 3) + 4 * i + r4] * NBP);
;         }
;         LDS_WAIT();
;         f32x4v a0 = {0.f, 0.f, 0.f, 0.f}, a1 = {0.f, 0.f, 0.f, 0.f};
; #pragma unroll
;         for (int ks = 0; ks < 4; ++ks) { const bf16x8 b0 = *(const LAS bf16x8*)(kfb + 64 * ks), b1 = *(const LAS bf16x8*)(kfb + 16 * 272 + 64 * ks);
;             a0 = __builtin_amdgcn_mfma_f32_16x16x32_bf16(qf[ks], b0, a0, 0, 0, 0); a1 = __builtin_amdgcn_mfma_f32_16x16x32_bf16(qf[ks], b1, a1, 0, 0, 0); }
;         LDS_WAIT();
;         const int bk = t5_bucket(sidx[kb] - t);
;         const bool valid = (32 * kb + n) < nsel;
; #pragma unroll
;         for (int g = 0; g < 4; ++g) { const float raw = upper ? a1[g] : a0[g]; const float v = valid ? raw + bl[g * 32 + bk] : -__builtin_inff(); lg[kb][g] = v; mx[g] = __builtin_fmaxf(mx[g], v); }
;     }
;     ...
;     for (int ch = 0; ch < 8; ++ch) {
; #pragma unroll
;         for (int i = 0; i < 8; ++i) *(LAS bf16x8*)(vdst + (4 * i) * 288) = vr[ch % 3][i];
;         if (ch + 3 < 8) {
; #pragma unroll
;             for (int i = 0; i < 8; ++i) vr[ch % 3][i] = *(const bf16x8*)(vg + (size_t)il[32 * (ch + 3) + 4 * i + r4] * NBP);
;         }
;         const bf16x8 pf = *(const LAS bf16x8*)(pfp + 32 * ch);
;         LDS_WAIT();
; #pragma unroll
;         for (int c = 0; c < 8; ++c) {
;             const s16x4 lo = vtr(vtb + c * 32), hh = vtr(vtb + 4 * 288 + c * 32);
;             o[c] = __builtin_amdgcn_mfma_f32_16x16x32_bf16(pf, (bf16x8){lo[0], lo[1], lo[2], lo[3], hh[0], hh[1], hh[2], hh[3]}, o[c], 0, 0, 0);
;         }
;         LDS_WAIT();
;     }
	v_mfma_f32_32x32x16_bf16 v[16:31], v[128:131], v[116:119], v[16:31]
	v_bfe_i32 v178, v174, 2, 1
	v_bfi_b32 v66, v178, v176, s13
	v_bfe_i32 v179, v174, 3, 1
	v_bfi_b32 v67, v179, v176, s13
	s_waitcnt lgkmcnt(12)
	v_mfma_f32_32x32x16_bf16 v[32:47], v[128:131], v[120:123], v[32:47]
	v_bfe_i32 v178, v174, 4, 1
	v_bfi_b32 v68, v178, v176, s13
	v_bfe_i32 v179, v174, 5, 1
	v_bfi_b32 v69, v179, v176, s13
	s_waitcnt lgkmcnt(9)
	v_mfma_f32_32x32x16_bf16 v[48:63], v[128:131], v[124:127], v[48:63]
	v_bfe_i32 v178, v174, 6, 1
	v_bfi_b32 v70, v178, v176, s13
	v_bfe_i32 v179, v174, 7, 1
	v_bfi_b32 v71, v179, v176, s13
	s_waitcnt lgkmcnt(6)
	v_mfma_f32_32x32x16_bf16 v[0:15], v[132:135], v[188:191], v[0:15]
	v_bfe_i32 v178, v174, 16, 1
	v_bfi_b32 v72, v178, v176, s13
	v_bfe_i32 v179, v174, 17, 1
	v_bfi_b32 v73, v179, v176, s13
	s_waitcnt lgkmcnt(4)
	v_mfma_f32_32x32x16_bf16 v[16:31], v[132:135], v[192:195], v[16:31]
	v_bfe_i32 v178, v174, 18, 1
	v_bfi_b32 v74, v178, v176, s13
	v_bfe_i32 v179, v174, 19, 1
	v_bfi_b32 v75, v179, v176, s13
	s_waitcnt lgkmcnt(2)
	v_mfma_f32_32x32x16_bf16 v[32:47], v[132:135], v[196:199], v[32:47]
	v_bfe_i32 v178, v174, 20, 1
	v_bfi_b32 v76, v178, v176, s13
	v_bfe_i32 v179, v174, 21, 1
	v_bfi_b32 v77, v179, v176, s13
	s_waitcnt lgkmcnt(0)
	v_mfma_f32_32x32x16_bf16 v[48:63], v[132:135], v[200:203], v[48:63]
	v_bfe_i32 v178, v174, 22, 1
	v_bfi_b32 v78, v178, v176, s13
	v_bfe_i32 v179, v174, 23, 1
	v_bfi_b32 v79, v179, v176, s13
	s_waitcnt lgkmcnt(0)
	s_barrier
	s_mov_b32 s25, s10
	s_mov_b32 s10, s11
	s_mov_b32 s11, s25
	v_add_u32_e32 v172, 8, v172
	s_mov_b32 s9, s24
	s_cmp_lt_u32 s9, s8
	s_cbranch_scc0 .Ldsa_exit
	v_add_u32_e32 v168, s10, v164
	ds_read_b128 v[112:115], v168 offset:0
	ds_read_b128 v[116:119], v168 offset:32
	ds_read_b128 v[120:123], v168 offset:64
	ds_read_b128 v[124:127], v168 offset:96
	ds_read_b128 v[188:191], v168 offset:128
	ds_read_b128 v[192:195], v168 offset:160
	ds_read_b128 v[196:199], v168 offset:192
	ds_read_b128 v[200:203], v168 offset:224
	v_add_u32_e32 v169, s10, v165
	v_add_u32_e32 v170, s11, v166
	v_add_u32_e32 v171, s11, v167
	s_add_u32 s24, s9, 1
	s_lshl_b32 s20, s9, 6
	s_add_u32 s27, s20, 32
	v_lshrrev_b32_e32 v182, v175, v182
	s_cmp_le_i32 s20, s19
	s_cbranch_scc1 .Ldsa_farA1
	s_lshl_b32 s26, s20, 2
	v_add_u32_e32 v179, s26, v177
	ds_read_b32 v64, v179 offset:0
	ds_read_b32 v65, v179 offset:4
	ds_read_b32 v66, v179 offset:8
	ds_read_b32 v67, v179 offset:12
	ds_read_b32 v68, v179 offset:16
	ds_read_b32 v69, v179 offset:20
	ds_read_b32 v70, v179 offset:24
	ds_read_b32 v71, v179 offset:28
	ds_read_b32 v72, v179 offset:64
	ds_read_b32 v73, v179 offset:68
	ds_read_b32 v74, v179 offset:72
	ds_read_b32 v75, v179 offset:76
	ds_read_b32 v76, v179 offset:80
	ds_read_b32 v77, v179 offset:84
	ds_read_b32 v78, v179 offset:88
	ds_read_b32 v79, v179 offset:92
	s_waitcnt lgkmcnt(0)
	v_bfe_i32 v178, v174, 0, 1
	v_bfi_b32 v64, v178, v64, s13
	v_bfe_i32 v178, v174, 1, 1
	v_bfi_b32 v65, v178, v65, s13
	v_bfe_i32 v178, v174, 2, 1
	v_bfi_b32 v66, v178, v66, s13
	v_bfe_i32 v178, v174, 3, 1
	v_bfi_b32 v67, v178, v67, s13
	v_bfe_i32 v178, v174, 4, 1
	v_bfi_b32 v68, v178, v68, s13
	v_bfe_i32 v178, v174, 5, 1
	v_bfi_b32 v69, v178, v69, s13
	v_bfe_i32 v178, v174, 6, 1
	v_bfi_b32 v70, v178, v70, s13
	v_bfe_i32 v178, v174, 7, 1
	v_bfi_b32 v71, v178, v71, s13
	v_bfe_i32 v178, v174, 16, 1
	v_bfi_b32 v72, v178, v72, s13
	v_bfe_i32 v178, v174, 17, 1
	v_bfi_b32 v73, v178, v73, s13
	v_bfe_i32 v178, v174, 18, 1
	v_bfi_b32 v74, v178, v74, s13
	v_bfe_i32 v178, v174, 19, 1
	v_bfi_b32 v75, v178, v75, s13
	v_bfe_i32 v178, v174, 20, 1
	v_bfi_b32 v76, v178, v76, s13
	v_bfe_i32 v178, v174, 21, 1
	v_bfi_b32 v77, v178, v77, s13
	v_bfe_i32 v178, v174, 22, 1
	v_bfi_b32 v78, v178, v78, s13
	v_bfe_i32 v178, v174, 23, 1
	v_bfi_b32 v79, v178, v79, s13
	s_nop 1
.Ldsa_farA1:
	s_waitcnt lgkmcnt(7)
	v_mfma_f32_32x32x16_bf16 v[64:79], v[112:115], v[80:83], v[64:79]
	ds_read_b128 v[112:115], v168 offset:8704
	v_bfe_i32 v178, v182, 0, 1
	v_bfi_b32 v128, v178, v176, s13
	v_bfe_i32 v179, v182, 1, 1
	v_bfi_b32 v129, v179, v176, s13
	s_waitcnt lgkmcnt(7)
	v_mfma_f32_32x32x16_bf16 v[64:79], v[116:119], v[84:87], v[64:79]
	ds_read_b128 v[116:119], v168 offset:8736
	v_bfe_i32 v178, v182, 2, 1
	v_bfi_b32 v130, v178, v176, s13
	v_bfe_i32 v179, v182, 3, 1
	v_bfi_b32 v131, v179, v176, s13
	global_load_dwordx4 v[214:217], v[160:161], off
	s_waitcnt lgkmcnt(7)
	v_mfma_f32_32x32x16_bf16 v[64:79], v[120:123], v[88:91], v[64:79]
	ds_read_b128 v[120:123], v168 offset:8768
	v_bfe_i32 v178, v182, 4, 1
	v_bfi_b32 v132, v178, v176, s13
	v_bfe_i32 v179, v182, 5, 1
	v_bfi_b32 v133, v179, v176, s13
	global_load_dwordx4 v[218:221], v[160:161], off offset:1024
	s_waitcnt lgkmcnt(7)
	v_mfma_f32_32x32x16_bf16 v[64:79], v[124:127], v[92:95], v[64:79]
	ds_read_b128 v[124:127], v168 offset:8800
	v_bfe_i32 v178, v182, 6, 1
	v_bfi_b32 v134, v178, v176, s13
	v_bfe_i32 v179, v182, 7, 1
	v_bfi_b32 v135, v179, v176, s13
	global_load_dwordx4 v[222:225], v[162:163], off
	s_waitcnt lgkmcnt(7)
	v_mfma_f32_32x32x16_bf16 v[64:79], v[188:191], v[96:99], v[64:79]
	ds_read_b128 v[188:191], v168 offset:8832
	v_bfe_i32 v178, v182, 16, 1
	v_bfi_b32 v136, v178, v176, s13
	v_bfe_i32 v179, v182, 17, 1
	v_bfi_b32 v137, v179, v176, s13
	global_load_dwordx4 v[226:229], v[162:163], off offset:1024
	s_waitcnt lgkmcnt(7)
	v_mfma_f32_32x32x16_bf16 v[64:79], v[192:195], v[100:103], v[64:79]
	ds_read_b128 v[192:195], v168 offset:8864
	v_bfe_i32 v178, v182, 18, 1
	v_bfi_b32 v138, v178, v176, s13
	v_bfe_i32 v179, v182, 19, 1
	v_bfi_b32 v139, v179, v176, s13
	s_add_u32 s40, s9, 3
	s_cmp_lt_u32 s40, s8
	s_cselect_b32 s40, s16, 0
	v_lshl_add_u64 v[160:161], v[160:161], 0, s[40:41]
	v_lshl_add_u64 v[162:163], v[162:163], 0, s[40:41]
	s_waitcnt lgkmcnt(7)
	v_mfma_f32_32x32x16_bf16 v[64:79], v[196:199], v[104:107], v[64:79]
	ds_read_b128 v[196:199], v168 offset:8896
	v_bfe_i32 v178, v182, 20, 1
	v_bfi_b32 v140, v178, v176, s13
	v_bfe_i32 v179, v182, 21, 1
	v_bfi_b32 v141, v179, v176, s13
	s_waitcnt lgkmcnt(7)
	v_mfma_f32_32x32x16_bf16 v[64:79], v[200:203], v[108:111], v[64:79]
	ds_read_b128 v[200:203], v168 offset:8928
	v_bfe_i32 v178, v182, 22, 1
	v_bfi_b32 v142, v178, v176, s13
	v_bfe_i32 v179, v182, 23, 1
	v_bfi_b32 v143, v179, v176, s13
	s_cmp_le_i32 s27, s19
	s_cbranch_scc1 .Ldsa_farB1
; #define LAS __attribute__((address_space(3)))
; #define LDS_WAIT() asm volatile("s_waitcnt lgkmcnt(0)" ::: "memory")
; __device__ __forceinline__ void dsa_unit(const bf16* QB, const int* SEL, bf16* AO, int b, int kvh, int t, LAS unsigned char* wl, int lane) {
;     ...
;         for (int ks = 0; ks < 4; ++ks) { const bf16x8 b0 = *(const LAS bf16x8*)(kfb + 64 * ks), b1 = *(const LAS bf16x8*)(kfb + 16 * 272 + 64 * ks);
;             a0 = __builtin_amdgcn_mfma_f32_16x16x32_bf16(qf[ks], b0, a0, 0, 0, 0); a1 = __builtin_amdgcn_mfma_f32_16x16x32_bf16(qf[ks], b1, a1, 0, 0, 0); }
;         LDS_WAIT();
;         const int bk = t5_bucket(sidx[kb] - t);
;         const bool valid = (32 * kb + n) < nsel;
; #pragma unroll
;         for (int g = 0; g < 4; ++g) { const float raw = upper ? a1[g] : a0[g]; const float v = valid ? raw + bl[g * 32 + bk] : -__builtin_inff(); lg[kb][g] = v; mx[g] = __builtin_fmaxf(mx[g], v); }
;     }
;     bf16x8 vr[3][8];
; #pragma unroll
;     for (int pb = 0; pb < 3; ++pb)
; #pragma unroll
;         for (int i = 0; i < 8; ++i) vr[pb][i] = *(const bf16x8*)(vg + (size_t)il[32 * pb + 4 * i + r4] * NBP);
; #pragma unroll
;     for (int g = 0; g < 4; ++g) {
;         float m = mx[g];
;         m = __builtin_fmaxf(m, __shfl_xor(m, 1)); m = __builtin_fmaxf(m, __shfl_xor(m, 2)); m = __builtin_fmaxf(m, __shfl_xor(m, 4)); m = __builtin_fmaxf(m, __shfl_xor(m, 8)); m = __builtin_fmaxf(m, __shfl_xor(m, 16));
;         float s = 0.f;
; #pragma unroll
;         for (int kb = 0; kb < 8; ++kb) { const float e = __builtin_amdgcn_exp2f(lg[kb][g] - m); lg[kb][g] = e; s += e; }
;     ...
;     for (int ch = 0; ch < 8; ++ch) {
; #pragma unroll
;         for (int i = 0; i < 8; ++i) *(LAS bf16x8*)(vdst + (4 * i) * 288) = vr[ch % 3][i];
;         if (ch + 3 < 8) {
; #pragma unroll
;             for (int i = 0; i < 8; ++i) vr[ch % 3][i] = *(const bf16x8*)(vg + (size_t)il[32 * (ch + 3) + 4 * i + r4] * NBP);
;         }
;         const bf16x8 pf = *(const LAS bf16x8*)(pfp + 32 * ch);
;         LDS_WAIT();
; #pragma unroll
;         for (int c = 0; c < 8; ++c) {
;             const s16x4 lo = vtr(vtb + c * 32), hh = vtr(vtb + 4 * 288 + c * 32);
;             o[c] = __builtin_amdgcn_mfma_f32_16x16x32_bf16(pf, (bf16x8){lo[0], lo[1], lo[2], lo[3], hh[0], hh[1], hh[2], hh[3]}, o[c], 0, 0, 0);
;         }
;         LDS_WAIT();
;     }
	s_lshl_b32 s26, s27, 2
	v_add_u32_e32 v179, s26, v177
	ds_read_b32 v128, v179 offset:0
	ds_read_b32 v129, v179 offset:4
	ds_read_b32 v130, v179 offset:8
	ds_read_b32 v131, v179 offset:12
	ds_read_b32 v132, v179 offset:16
	ds_read_b32 v133, v179 offset:20
	ds_read_b32 v134, v179 offset:24
	ds_read_b32 v135, v179 offset:28
	ds_read_b32 v136, v179 offset:64
	ds_read_b32 v137, v179 offset:68
	ds_read_b32 v138, v179 offset:72
	ds_read_b32 v139, v179 offset:76
	ds_read_b32 v140, v179 offset:80
	ds_read_b32 v141, v179 offset:84
	ds_read_b32 v142, v179 offset:88
	ds_read_b32 v143, v179 offset:92
	s_waitcnt lgkmcnt(0)
	v_bfe_i32 v178, v182, 0, 1
	v_bfi_b32 v128, v178, v128, s13
	v_bfe_i32 v178, v182, 1, 1
	v_bfi_b32 v129, v178, v129, s13
	v_bfe_i32 v178, v182, 2, 1
	v_bfi_b32 v130, v178, v130, s13
	v_bfe_i32 v178, v182, 3, 1
	v_bfi_b32 v131, v178, v131, s13
	v_bfe_i32 v178, v182, 4, 1
	v_bfi_b32 v132, v178, v132, s13
	v_bfe_i32 v178, v182, 5, 1
	v_bfi_b32 v133, v178, v133, s13
	v_bfe_i32 v178, v182, 6, 1
	v_bfi_b32 v134, v178, v134, s13
	v_bfe_i32 v178, v182, 7, 1
	v_bfi_b32 v135, v178, v135, s13
	v_bfe_i32 v178, v182, 16, 1
	v_bfi_b32 v136, v178, v136, s13
	v_bfe_i32 v178, v182, 17, 1
	v_bfi_b32 v137, v178, v137, s13
	v_bfe_i32 v178, v182, 18, 1
	v_bfi_b32 v138, v178, v138, s13
	v_bfe_i32 v178, v182, 19, 1
	v_bfi_b32 v139, v178, v139, s13
	v_bfe_i32 v178, v182, 20, 1
	v_bfi_b32 v140, v178, v140, s13
	v_bfe_i32 v178, v182, 21, 1
	v_bfi_b32 v141, v178, v141, s13
	v_bfe_i32 v178, v182, 22, 1
	v_bfi_b32 v142, v178, v142, s13
	v_bfe_i32 v178, v182, 23, 1
	v_bfi_b32 v143, v178, v143, s13
	s_nop 1
.Ldsa_farB1:
	ds_read_b32 v174, v172 offset:8
	ds_read_b32 v182, v172 offset:12
	s_nop 1
	s_waitcnt lgkmcnt(9)
	v_mfma_f32_32x32x16_bf16 v[128:143], v[112:115], v[80:83], v[128:143]
	ds_read_b64_tr_b16 v[112:113], v169 offset:0
	ds_read_b64_tr_b16 v[114:115], v169 offset:1280
	v_exp_f32_e32 v64, v64
	v_exp_f32_e32 v65, v65
	v_add_f32_e32 v173, v173, v64
	v_add_f32_e32 v173, v173, v65
	v_cvt_pk_bf16_f32 v64, v64, v65
	s_waitcnt lgkmcnt(10)
	v_mfma_f32_32x32x16_bf16 v[128:143], v[116:119], v[84:87], v[128:143]
	ds_read_b64_tr_b16 v[116:117], v169 offset:64
	ds_read_b64_tr_b16 v[118:119], v169 offset:1344
	v_exp_f32_e32 v66, v66
	v_exp_f32_e32 v67, v67
	v_add_f32_e32 v173, v173, v66
	v_add_f32_e32 v173, v173, v67
	v_cvt_pk_bf16_f32 v65, v66, v67
	s_waitcnt lgkmcnt(11)
	v_mfma_f32_32x32x16_bf16 v[128:143], v[120:123], v[88:91], v[128:143]
	ds_read_b64_tr_b16 v[120:121], v169 offset:128
	ds_read_b64_tr_b16 v[122:123], v169 offset:1408
	v_exp_f32_e32 v68, v68
	v_exp_f32_e32 v69, v69
	v_add_f32_e32 v173, v173, v68
	v_add_f32_e32 v173, v173, v69
	v_cvt_pk_bf16_f32 v66, v68, v69
	s_waitcnt lgkmcnt(12)
	v_mfma_f32_32x32x16_bf16 v[128:143], v[124:127], v[92:95], v[128:143]
	ds_read_b64_tr_b16 v[124:125], v169 offset:192
	ds_read_b64_tr_b16 v[126:127], v169 offset:1472
	v_exp_f32_e32 v70, v70
	v_exp_f32_e32 v71, v71
	v_add_f32_e32 v173, v173, v70
	v_add_f32_e32 v173, v173, v71
	v_cvt_pk_bf16_f32 v67, v70, v71
	s_waitcnt lgkmcnt(13)
	v_mfma_f32_32x32x16_bf16 v[128:143], v[188:191], v[96:99], v[128:143]
	ds_read_b64_tr_b16 v[188:189], v169 offset:5120
	ds_read_b64_tr_b16 v[190:191], v169 offset:6400
	v_exp_f32_e32 v72, v72
	v_exp_f32_e32 v73, v73
	v_add_f32_e32 v173, v173, v72
	v_add_f32_e32 v173, v173, v73
	v_cvt_pk_bf16_f32 v68, v72, v73
	s_waitcnt lgkmcnt(14)
	v_mfma_f32_32x32x16_bf16 v[128:143], v[192:195], v[100:103], v[128:143]
	ds_read_b64_tr_b16 v[192:193], v169 offset:5184
	ds_read_b64_tr_b16 v[194:195], v169 offset:6464
	v_exp_f32_e32 v74, v74
	v_exp_f32_e32 v75, v75
	v_add_f32_e32 v173, v173, v74
	v_add_f32_e32 v173, v173, v75
	v_cvt_pk_bf16_f32 v69, v74, v75
	s_waitcnt lgkmcnt(15)
	v_mfma_f32_32x32x16_bf16 v[128:143], v[196:199], v[104:107], v[128:143]
	ds_read_b64_tr_b16 v[196:197], v169 offset:5248
	ds_read_b64_tr_b16 v[198:199], v169 offset:6528
	v_exp_f32_e32 v76, v76
	v_exp_f32_e32 v77, v77
	v_add_f32_e32 v173, v173, v76
	v_add_f32_e32 v173, v173, v77
	v_cvt_pk_bf16_f32 v70, v76, v77
	s_waitcnt lgkmcnt(15)
	v_mfma_f32_32x32x16_bf16 v[128:143], v[200:203], v[108:111], v[128:143]
	ds_read_b64_tr_b16 v[200:201], v169 offset:5312
	ds_read_b64_tr_b16 v[202:203], v169 offset:6592
	v_exp_f32_e32 v78, v78
	v_exp_f32_e32 v79, v79
	v_add_f32_e32 v173, v173, v78
	v_add_f32_e32 v173, v173, v79
	v_cvt_pk_bf16_f32 v71, v78, v79
	s_waitcnt lgkmcnt(14)
	v_mfma_f32_32x32x16_bf16 v[0:15], v[64:67], v[112:115], v[0:15]
	ds_read_b64_tr_b16 v[112:113], v169 offset:10240
	ds_read_b64_tr_b16 v[114:115], v169 offset:11520
	s_waitcnt vmcnt(4)
	ds_write_b128 v170, v[144:147]
	v_exp_f32_e32 v128, v128
	v_exp_f32_e32 v129, v129
	v_add_f32_e32 v173, v173, v128
	v_add_f32_e32 v173, v173, v129
	v_cvt_pk_bf16_f32 v128, v128, v129
	s_waitcnt lgkmcnt(15)
	v_mfma_f32_32x32x16_bf16 v[16:31], v[64:67], v[116:119], v[16:31]
	ds_read_b64_tr_b16 v[116:117], v169 offset:10304
	ds_read_b64_tr_b16 v[118:119], v169 offset:11584
	ds_write_b128 v171, v[148:151]
	v_exp_f32_e32 v130, v130
	v_exp_f32_e32 v131, v131
	v_add_f32_e32 v173, v173, v130
	v_add_f32_e32 v173, v173, v131
	v_cvt_pk_bf16_f32 v129, v130, v131
	s_waitcnt lgkmcnt(15)
	v_mfma_f32_32x32x16_bf16 v[32:47], v[64:67], v[120:123], v[32:47]
	ds_read_b64_tr_b16 v[120:121], v169 offset:10368
	ds_read_b64_tr_b16 v[122:123], v169 offset:11648
	ds_write_b128 v170, v[152:155] offset:8704
	v_exp_f32_e32 v132, v132
	v_exp_f32_e32 v133, v133
	v_add_f32_e32 v173, v173, v132
	v_add_f32_e32 v173, v173, v133
	v_cvt_pk_bf16_f32 v130, v132, v133
	s_waitcnt lgkmcnt(15)
; #define LAS __attribute__((address_space(3)))
; __device__ __forceinline__ unsigned pk2(float lo, float hi) { return pg8::cvt_pk_bf16(lo, hi); }
; #define LDS_WAIT() asm volatile("s_waitcnt lgkmcnt(0)" ::: "memory")
; __device__ __forceinline__ void dsa_unit(const bf16* QB, const int* SEL, bf16* AO, int b, int kvh, int t, LAS unsigned char* wl, int lane) {
;     ...
;         for (int kb = 0; kb < 8; ++kb) { const float e = __builtin_amdgcn_exp2f(lg[kb][g] - m); lg[kb][g] = e; s += e; }
;         s += __shfl_xor(s, 1); s += __shfl_xor(s, 2); s += __shfl_xor(s, 4); s += __shfl_xor(s, 8); s += __shfl_xor(s, 16);
;         const float inv = 1.0f / s;
; #pragma unroll
;         for (int kb = 0; kb < 8; ++kb) if ((kb >> 2) == hi) pT[g * 256 + 32 * kb + n] = (bf16)(pk2(lg[kb][g] * inv, 0.f) & 0xffffu);
;     }
;     f32x4v o[8];
; #pragma unroll
;     for (int c = 0; c < 8; ++c) o[c] = (f32x4v){0.f, 0.f, 0.f, 0.f};
;     const LAS unsigned char* vtb = buf + (8 * kq + (l15 >> 2)) * 288 + (lane & 3) * 8;
;     LAS unsigned char* vdst = buf + r4 * 288 + c16 * 16;
;     const LAS bf16* pfp = pT + (l15 & 3) * 256 + 8 * kq;
; #pragma unroll
;     for (int ch = 0; ch < 8; ++ch) {
; #pragma unroll
;         for (int i = 0; i < 8; ++i) *(LAS bf16x8*)(vdst + (4 * i) * 288) = vr[ch % 3][i];
;         if (ch + 3 < 8) {
; #pragma unroll
;             for (int i = 0; i < 8; ++i) vr[ch % 3][i] = *(const bf16x8*)(vg + (size_t)il[32 * (ch + 3) + 4 * i + r4] * NBP);
;         }
;         const bf16x8 pf = *(const LAS bf16x8*)(pfp + 32 * ch);
;         LDS_WAIT();
; #pragma unroll
;         for (int c = 0; c < 8; ++c) {
;             const s16x4 lo = vtr(vtb + c * 32), hh = vtr(vtb + 4 * 288 + c * 32);
;             o[c] = __builtin_amdgcn_mfma_f32_16x16x32_bf16(pf, (bf16x8){lo[0], lo[1], lo[2], lo[3], hh[0], hh[1], hh[2], hh[3]}, o[c], 0, 0, 0);
;         }
;         LDS_WAIT();
;     }
;     bf16* op = AO + row * D + (kvh * 4) * 128 + 16 * kq + l15;
; #pragma unroll
;     for (int i = 0; i < 2; ++i)
; #pragma unroll
;         for (int g = 0; g < 4; ++g) {
;             const float v = (kq == 0) ? o[4 * i][g] : (kq == 1) ? o[4 * i + 1][g] : (kq == 2) ? o[4 * i + 2][g] : o[4 * i + 3][g];
;             op[g * 128 + 64 * i] = (bf16)(pk2(v, 0.f) & 0xffffu);
;         }
	v_mfma_f32_32x32x16_bf16 v[48:63], v[64:67], v[124:127], v[48:63]
	ds_read_b64_tr_b16 v[124:125], v169 offset:10432
	ds_read_b64_tr_b16 v[126:127], v169 offset:11712
	ds_write_b128 v171, v[156:159] offset:10240
	v_exp_f32_e32 v134, v134
	v_exp_f32_e32 v135, v135
	v_add_f32_e32 v173, v173, v134
	v_add_f32_e32 v173, v173, v135
	v_cvt_pk_bf16_f32 v131, v134, v135
	v_mfma_f32_32x32x16_bf16 v[0:15], v[68:71], v[188:191], v[0:15]
	ds_read_b64_tr_b16 v[188:189], v169 offset:15360
	ds_read_b64_tr_b16 v[190:191], v169 offset:16640
	s_nop 0
	v_exp_f32_e32 v136, v136
	v_exp_f32_e32 v137, v137
	v_add_f32_e32 v173, v173, v136
	v_add_f32_e32 v173, v173, v137
	v_cvt_pk_bf16_f32 v132, v136, v137
	s_waitcnt lgkmcnt(15)
	v_mfma_f32_32x32x16_bf16 v[16:31], v[68:71], v[192:195], v[16:31]
	ds_read_b64_tr_b16 v[192:193], v169 offset:15424
	ds_read_b64_tr_b16 v[194:195], v169 offset:16704
	s_nop 0
	v_exp_f32_e32 v138, v138
	v_exp_f32_e32 v139, v139
	v_add_f32_e32 v173, v173, v138
	v_add_f32_e32 v173, v173, v139
	v_cvt_pk_bf16_f32 v133, v138, v139
	v_mfma_f32_32x32x16_bf16 v[32:47], v[68:71], v[196:199], v[32:47]
	ds_read_b64_tr_b16 v[196:197], v169 offset:15488
	ds_read_b64_tr_b16 v[198:199], v169 offset:16768
	s_nop 0
	v_exp_f32_e32 v140, v140
	v_exp_f32_e32 v141, v141
	v_add_f32_e32 v173, v173, v140
	v_add_f32_e32 v173, v173, v141
	v_cvt_pk_bf16_f32 v134, v140, v141
	s_waitcnt lgkmcnt(15)
	v_mfma_f32_32x32x16_bf16 v[48:63], v[68:71], v[200:203], v[48:63]
	ds_read_b64_tr_b16 v[200:201], v169 offset:15552
	ds_read_b64_tr_b16 v[202:203], v169 offset:16832
	s_nop 0
	v_exp_f32_e32 v142, v142
	v_exp_f32_e32 v143, v143
	v_add_f32_e32 v173, v173, v142
	v_add_f32_e32 v173, v173, v143
	v_cvt_pk_bf16_f32 v135, v142, v143
	v_lshrrev_b32_e32 v174, v175, v174
	v_mfma_f32_32x32x16_bf16 v[0:15], v[128:131], v[112:115], v[0:15]
	v_bfe_i32 v178, v174, 0, 1
	v_bfi_b32 v64, v178, v176, s13
	v_bfe_i32 v179, v174, 1, 1
	v_bfi_b32 v65, v179, v176, s13
	s_waitcnt lgkmcnt(15)
	v_mfma_f32_32x32x16_bf16 v[16:31], v[128:131], v[116:119], v[16:31]
	v_bfe_i32 v178, v174, 2, 1
	v_bfi_b32 v66, v178, v176, s13
	v_bfe_i32 v179, v174, 3, 1
	v_bfi_b32 v67, v179, v176, s13
	s_waitcnt lgkmcnt(12)
	v_mfma_f32_32x32x16_bf16 v[32:47], v[128:131], v[120:123], v[32:47]
	v_bfe_i32 v178, v174, 4, 1
	v_bfi_b32 v68, v178, v176, s13
	v_bfe_i32 v179, v174, 5, 1
	v_bfi_b32 v69, v179, v176, s13
	s_waitcnt lgkmcnt(9)
	v_mfma_f32_32x32x16_bf16 v[48:63], v[128:131], v[124:127], v[48:63]
	v_bfe_i32 v178, v174, 6, 1
	v_bfi_b32 v70, v178, v176, s13
	v_bfe_i32 v179, v174, 7, 1
	v_bfi_b32 v71, v179, v176, s13
	s_waitcnt lgkmcnt(6)
	v_mfma_f32_32x32x16_bf16 v[0:15], v[132:135], v[188:191], v[0:15]
	v_bfe_i32 v178, v174, 16, 1
	v_bfi_b32 v72, v178, v176, s13
	v_bfe_i32 v179, v174, 17, 1
	v_bfi_b32 v73, v179, v176, s13
	s_waitcnt lgkmcnt(4)
	v_mfma_f32_32x32x16_bf16 v[16:31], v[132:135], v[192:195], v[16:31]
	v_bfe_i32 v178, v174, 18, 1
	v_bfi_b32 v74, v178, v176, s13
	v_bfe_i32 v179, v174, 19, 1
	v_bfi_b32 v75, v179, v176, s13
	s_waitcnt lgkmcnt(2)
	v_mfma_f32_32x32x16_bf16 v[32:47], v[132:135], v[196:199], v[32:47]
	v_bfe_i32 v178, v174, 20, 1
	v_bfi_b32 v76, v178, v176, s13
	v_bfe_i32 v179, v174, 21, 1
	v_bfi_b32 v77, v179, v176, s13
	s_waitcnt lgkmcnt(0)
	v_mfma_f32_32x32x16_bf16 v[48:63], v[132:135], v[200:203], v[48:63]
	v_bfe_i32 v178, v174, 22, 1
	v_bfi_b32 v78, v178, v176, s13
	v_bfe_i32 v179, v174, 23, 1
	v_bfi_b32 v79, v179, v176, s13
	s_waitcnt lgkmcnt(0)
	s_barrier
	s_mov_b32 s25, s10
	s_mov_b32 s10, s11
	s_mov_b32 s11, s25
	v_add_u32_e32 v172, 8, v172
	s_mov_b32 s9, s24
	s_cmp_lt_u32 s9, s8
	s_cbranch_scc1 .Ldsa_it
.Ldsa_exit:
	s_waitcnt vmcnt(0)
	v_xor_b32_e32 v178, 32, v206
	v_lshlrev_b32_e32 v178, 2, v178
	ds_bpermute_b32 v179, v178, v173
	s_waitcnt lgkmcnt(0)
	v_add_f32_e32 v173, v173, v179
	v_rcp_f32_e32 v173, v173
	s_nop 0
	v_and_b32_e32 v178, 31, v206
	v_lshlrev_b32_e32 v178, 2, v178
	s_lshl_b32 s24, s0, 7
	s_add_u32 s24, s24, 0x1b000
	v_add_u32_e32 v178, s24, v178
	ds_write_b32 v178, v173
	v_lshl_add_u32 v179, v175, 1, s24
	s_waitcnt lgkmcnt(0)
	ds_read_b128 v[112:115], v179 offset:0
	ds_read_b128 v[116:119], v179 offset:32
	ds_read_b128 v[120:123], v179 offset:64
	ds_read_b128 v[124:127], v179 offset:96
	v_and_b32_e32 v178, 31, v206
	v_lshlrev_b32_e32 v178, 1, v178
	v_mul_u32_u24_e32 v179, 0x88, v175
	v_add3_u32 v178, v178, v179, s45
	v_lshrrev_b32_e32 v179, 4, v206
	v_mul_u32_u24_e32 v182, 0x110, v179
	v_and_b32_e32 v172, 15, v206
	v_lshl_add_u32 v182, v172, 4, v182
	v_add_u32_e32 v174, s45, v182
	s_add_u32 s24, s44, s7
	s_add_u32 s24, s24, s4
	s_lshr_b32 s25, s24, 20
	s_lshl_b32 s24, s24, 12
	s_add_u32 s24, s24, s67
	s_addc_u32 s25, s25, s85
	s_lshl_b32 s26, s5, 10
	s_add_u32 s24, s24, s26
	s_addc_u32 s25, s25, 0
	v_lshlrev_b32_e32 v179, 8, v179
	v_lshl_add_u32 v182, v172, 4, v179
	v_lshl_add_u64 v[144:145], s[24:25], 0, v[182:183]
	s_movk_i32 s26, 0x1000
	s_mov_b32 s27, 0
	s_waitcnt lgkmcnt(0)
; #define LAS __attribute__((address_space(3)))
; __device__ __forceinline__ unsigned pk2(float lo, float hi) { return pg8::cvt_pk_bf16(lo, hi); }
; #define LDS_WAIT() asm volatile("s_waitcnt lgkmcnt(0)" ::: "memory")
; __device__ __forceinline__ s16x4 vtr(const LAS unsigned char* p) { return __builtin_bit_cast(s16x4, __builtin_amdgcn_ds_read_tr16_b64_v4i16((LAS s16x4*)p)); }
; __device__ __forceinline__ void dsa_unit(const bf16* QB, const int* SEL, bf16* AO, int b, int kvh, int t, LAS unsigned char* wl, int lane) {
;     ...
;         const float inv = 1.0f / s;
; #pragma unroll
;         for (int kb = 0; kb < 8; ++kb) if ((kb >> 2) == hi) pT[g * 256 + 32 * kb + n] = (bf16)(pk2(lg[kb][g] * inv, 0.f) & 0xffffu);
;     }
;     f32x4v o[8];
; #pragma unroll
;     for (int c = 0; c < 8; ++c) o[c] = (f32x4v){0.f, 0.f, 0.f, 0.f};
;     const LAS unsigned char* vtb = buf + (8 * kq + (l15 >> 2)) * 288 + (lane & 3) * 8;
;     LAS unsigned char* vdst = buf + r4 * 288 + c16 * 16;
;     const LAS bf16* pfp = pT + (l15 & 3) * 256 + 8 * kq;
; #pragma unroll
;     for (int ch = 0; ch < 8; ++ch) {
; #pragma unroll
;         for (int i = 0; i < 8; ++i) *(LAS bf16x8*)(vdst + (4 * i) * 288) = vr[ch % 3][i];
;         if (ch + 3 < 8) {
; #pragma unroll
;             for (int i = 0; i < 8; ++i) vr[ch % 3][i] = *(const bf16x8*)(vg + (size_t)il[32 * (ch + 3) + 4 * i + r4] * NBP);
;         }
;         const bf16x8 pf = *(const LAS bf16x8*)(pfp + 32 * ch);
;         LDS_WAIT();
; #pragma unroll
;         for (int c = 0; c < 8; ++c) {
;             const s16x4 lo = vtr(vtb + c * 32), hh = vtr(vtb + 4 * 288 + c * 32);
;             o[c] = __builtin_amdgcn_mfma_f32_16x16x32_bf16(pf, (bf16x8){lo[0], lo[1], lo[2], lo[3], hh[0], hh[1], hh[2], hh[3]}, o[c], 0, 0, 0);
;         }
;         LDS_WAIT();
;     }
;     bf16* op = AO + row * D + (kvh * 4) * 128 + 16 * kq + l15;
; #pragma unroll
;     for (int i = 0; i < 2; ++i)
; #pragma unroll
;         for (int g = 0; g < 4; ++g) {
;             const float v = (kq == 0) ? o[4 * i][g] : (kq == 1) ? o[4 * i + 1][g] : (kq == 2) ? o[4 * i + 2][g] : o[4 * i + 3][g];
;             op[g * 128 + 64 * i] = (bf16)(pk2(v, 0.f) & 0xffffu);
;         }
	v_pk_mul_f32 v[0:1], v[0:1], v[112:113]
	v_pk_mul_f32 v[2:3], v[2:3], v[114:115]
	v_pk_mul_f32 v[4:5], v[4:5], v[116:117]
	v_pk_mul_f32 v[6:7], v[6:7], v[118:119]
	v_pk_mul_f32 v[8:9], v[8:9], v[120:121]
	v_pk_mul_f32 v[10:11], v[10:11], v[122:123]
	v_pk_mul_f32 v[12:13], v[12:13], v[124:125]
	v_pk_mul_f32 v[14:15], v[14:15], v[126:127]
	v_pk_mul_f32 v[16:17], v[16:17], v[112:113]
	v_pk_mul_f32 v[18:19], v[18:19], v[114:115]
	v_pk_mul_f32 v[20:21], v[20:21], v[116:117]
	v_pk_mul_f32 v[22:23], v[22:23], v[118:119]
	v_pk_mul_f32 v[24:25], v[24:25], v[120:121]
	v_pk_mul_f32 v[26:27], v[26:27], v[122:123]
	v_pk_mul_f32 v[28:29], v[28:29], v[124:125]
	v_pk_mul_f32 v[30:31], v[30:31], v[126:127]
	v_pk_mul_f32 v[32:33], v[32:33], v[112:113]
	v_pk_mul_f32 v[34:35], v[34:35], v[114:115]
	v_pk_mul_f32 v[36:37], v[36:37], v[116:117]
	v_pk_mul_f32 v[38:39], v[38:39], v[118:119]
	v_pk_mul_f32 v[40:41], v[40:41], v[120:121]
	v_pk_mul_f32 v[42:43], v[42:43], v[122:123]
	v_pk_mul_f32 v[44:45], v[44:45], v[124:125]
	v_pk_mul_f32 v[46:47], v[46:47], v[126:127]
	v_pk_mul_f32 v[48:49], v[48:49], v[112:113]
	v_pk_mul_f32 v[50:51], v[50:51], v[114:115]
	v_pk_mul_f32 v[52:53], v[52:53], v[116:117]
	v_pk_mul_f32 v[54:55], v[54:55], v[118:119]
	v_pk_mul_f32 v[56:57], v[56:57], v[120:121]
	v_pk_mul_f32 v[58:59], v[58:59], v[122:123]
	v_pk_mul_f32 v[60:61], v[60:61], v[124:125]
	v_pk_mul_f32 v[62:63], v[62:63], v[126:127]
	v_cvt_pk_bf16_f32 v64, v0, v1
	v_cvt_pk_bf16_f32 v65, v2, v3
	v_cvt_pk_bf16_f32 v66, v4, v5
	v_cvt_pk_bf16_f32 v67, v6, v7
	v_cvt_pk_bf16_f32 v68, v8, v9
	v_cvt_pk_bf16_f32 v69, v10, v11
	v_cvt_pk_bf16_f32 v70, v12, v13
	v_cvt_pk_bf16_f32 v71, v14, v15
	ds_write_b16 v178, v64 offset:0
	ds_write_b16_d16_hi v178, v64 offset:272
	ds_write_b16 v178, v65 offset:544
	ds_write_b16_d16_hi v178, v65 offset:816
	ds_write_b16 v178, v66 offset:2176
	ds_write_b16_d16_hi v178, v66 offset:2448
	ds_write_b16 v178, v67 offset:2720
	ds_write_b16_d16_hi v178, v67 offset:2992
	ds_write_b16 v178, v68 offset:4352
	ds_write_b16_d16_hi v178, v68 offset:4624
	ds_write_b16 v178, v69 offset:4896
	ds_write_b16_d16_hi v178, v69 offset:5168
	ds_write_b16 v178, v70 offset:6528
	ds_write_b16_d16_hi v178, v70 offset:6800
	ds_write_b16 v178, v71 offset:7072
	ds_write_b16_d16_hi v178, v71 offset:7344
	v_cvt_pk_bf16_f32 v72, v16, v17
	v_cvt_pk_bf16_f32 v73, v18, v19
	v_cvt_pk_bf16_f32 v74, v20, v21
	v_cvt_pk_bf16_f32 v75, v22, v23
	v_cvt_pk_bf16_f32 v76, v24, v25
	v_cvt_pk_bf16_f32 v77, v26, v27
	v_cvt_pk_bf16_f32 v78, v28, v29
	v_cvt_pk_bf16_f32 v79, v30, v31
	ds_write_b16 v178, v72 offset:64
	ds_write_b16_d16_hi v178, v72 offset:336
	ds_write_b16 v178, v73 offset:608
	ds_write_b16_d16_hi v178, v73 offset:880
	ds_write_b16 v178, v74 offset:2240
	ds_write_b16_d16_hi v178, v74 offset:2512
	ds_write_b16 v178, v75 offset:2784
	ds_write_b16_d16_hi v178, v75 offset:3056
	ds_write_b16 v178, v76 offset:4416
	ds_write_b16_d16_hi v178, v76 offset:4688
	ds_write_b16 v178, v77 offset:4960
	ds_write_b16_d16_hi v178, v77 offset:5232
	ds_write_b16 v178, v78 offset:6592
	ds_write_b16_d16_hi v178, v78 offset:6864
	ds_write_b16 v178, v79 offset:7136
	ds_write_b16_d16_hi v178, v79 offset:7408
	v_cvt_pk_bf16_f32 v128, v32, v33
	v_cvt_pk_bf16_f32 v129, v34, v35
	v_cvt_pk_bf16_f32 v130, v36, v37
	v_cvt_pk_bf16_f32 v131, v38, v39
	v_cvt_pk_bf16_f32 v132, v40, v41
	v_cvt_pk_bf16_f32 v133, v42, v43
	v_cvt_pk_bf16_f32 v134, v44, v45
	v_cvt_pk_bf16_f32 v135, v46, v47
	ds_write_b16 v178, v128 offset:128
	ds_write_b16_d16_hi v178, v128 offset:400
	ds_write_b16 v178, v129 offset:672
	ds_write_b16_d16_hi v178, v129 offset:944
	ds_write_b16 v178, v130 offset:2304
	ds_write_b16_d16_hi v178, v130 offset:2576
	ds_write_b16 v178, v131 offset:2848
	ds_write_b16_d16_hi v178, v131 offset:3120
	ds_write_b16 v178, v132 offset:4480
	ds_write_b16_d16_hi v178, v132 offset:4752
	ds_write_b16 v178, v133 offset:5024
	ds_write_b16_d16_hi v178, v133 offset:5296
	ds_write_b16 v178, v134 offset:6656
	ds_write_b16_d16_hi v178, v134 offset:6928
	ds_write_b16 v178, v135 offset:7200
	ds_write_b16_d16_hi v178, v135 offset:7472
	v_cvt_pk_bf16_f32 v136, v48, v49
	v_cvt_pk_bf16_f32 v137, v50, v51
	v_cvt_pk_bf16_f32 v138, v52, v53
	v_cvt_pk_bf16_f32 v139, v54, v55
	v_cvt_pk_bf16_f32 v140, v56, v57
	v_cvt_pk_bf16_f32 v141, v58, v59
	v_cvt_pk_bf16_f32 v142, v60, v61
	v_cvt_pk_bf16_f32 v143, v62, v63
	ds_write_b16 v178, v136 offset:192
	ds_write_b16_d16_hi v178, v136 offset:464
	ds_write_b16 v178, v137 offset:736
	ds_write_b16_d16_hi v178, v137 offset:1008
	ds_write_b16 v178, v138 offset:2368
	ds_write_b16_d16_hi v178, v138 offset:2640
	ds_write_b16 v178, v139 offset:2912
	ds_write_b16_d16_hi v178, v139 offset:3184
	ds_write_b16 v178, v140 offset:4544
	ds_write_b16_d16_hi v178, v140 offset:4816
	ds_write_b16 v178, v141 offset:5088
	ds_write_b16_d16_hi v178, v141 offset:5360
	ds_write_b16 v178, v142 offset:6720
	ds_write_b16_d16_hi v178, v142 offset:6992
	ds_write_b16 v178, v143 offset:7264
	ds_write_b16_d16_hi v178, v143 offset:7536
	s_waitcnt lgkmcnt(0)
	ds_read_b128 v[80:83], v174 offset:0
	ds_read_b128 v[84:87], v174 offset:1088
	ds_read_b128 v[88:91], v174 offset:2176
	ds_read_b128 v[92:95], v174 offset:3264
	ds_read_b128 v[96:99], v174 offset:4352
	ds_read_b128 v[100:103], v174 offset:5440
	ds_read_b128 v[104:107], v174 offset:6528
	ds_read_b128 v[108:111], v174 offset:7616
	s_waitcnt lgkmcnt(7)
	global_store_dwordx4 v[144:145], v[80:83], off
	v_lshl_add_u64 v[144:145], v[144:145], 0, s[26:27]
	s_waitcnt lgkmcnt(6)
	global_store_dwordx4 v[144:145], v[84:87], off
	v_lshl_add_u64 v[144:145], v[144:145], 0, s[26:27]
	s_waitcnt lgkmcnt(5)
	global_store_dwordx4 v[144:145], v[88:91], off
	v_lshl_add_u64 v[144:145], v[144:145], 0, s[26:27]
	s_waitcnt lgkmcnt(4)
	global_store_dwordx4 v[144:145], v[92:95], off
	v_lshl_add_u64 v[144:145], v[144:145], 0, s[26:27]
	s_waitcnt lgkmcnt(3)
	global_store_dwordx4 v[144:145], v[96:99], off
	v_lshl_add_u64 v[144:145], v[144:145], 0, s[26:27]
	s_waitcnt lgkmcnt(2)
	global_store_dwordx4 v[144:145], v[100:103], off
	v_lshl_add_u64 v[144:145], v[144:145], 0, s[26:27]
	s_waitcnt lgkmcnt(1)
	global_store_dwordx4 v[144:145], v[104:107], off
	v_lshl_add_u64 v[144:145], v[144:145], 0, s[26:27]
	s_waitcnt lgkmcnt(0)
	global_store_dwordx4 v[144:145], v[108:111], off
	s_add_u32 s21, s21, 1
	s_cmp_lt_u32 s21, 2
	s_cbranch_scc1 .Ldsa_half
	s_add_u32 s3, s3, s2
	s_branch .Ldsa_unit
